# final norm phase: row-invariant final-norm weights loaded once per wave; the 8 output stores of a row no longer wait on each other
# baseline (speedup 1.0000x reference)
; #define GAS __attribute__((address_space(1)))
; __device__ __forceinline__ void final_phase(Frame& F, int nsplit, const float* part) {
;     const int gw = blockIdx.x * NWAVES + F.wave, NGW = F.G * NWAVES; const float* ssq = WSP(float, WS_SSQ);
;     for (int m = gw; m < M; m += NGW) { const bool smp = m >= SEQ; f32x4 v[8];
;         float s = row_xb_plus_parts(WSP(bf16, WS_H), m, part + (size_t)(smp ? m - SEQ : 0) * D, smp ? nsplit : 0, v, F.lane);
;         if (!smp) { const f32x4 a = *(const f32x4*)(ssq + (size_t)m * 8), b = *(const f32x4*)(ssq + (size_t)m * 8 + 4); s = ((a.x + a.y) + (a.z + a.w)) + ((b.x + b.y) + (b.z + b.w)); }
;         const float rstd = 1.0f / sqrtf(s * (1.f / D) + EPS);
;         const GAS f32x4* wr = (const GAS f32x4*)F.final_norm_w + F.lane; GAS f32x4* o = (GAS f32x4*)(F.out + O_YP + (size_t)m * D) + F.lane;
; #pragma unroll
;         for (int j = 0; j < 8; ++j) __builtin_nontemporal_store(v[j] * rstd * wr[64 * j], o + 64 * j); }
; }
.LBB0_2480:
	s_cmp_lt_i32 s92, 20
	s_cselect_b64 s[0:1], -1, 0
	s_and_b64 s[0:1], s[0:1], s[2:3]
	s_andn2_b64 vcc, exec, s[0:1]
	s_cbranch_vccnz .LBB0_2493
	s_lshl_b32 s0, s82, 3
	s_add_i32 s2, s96, s0
	s_cmpk_gt_i32 s2, 0x41ff
	s_cbranch_scc1 .LBB0_2493
	v_mbcnt_lo_u32_b32 v1, -1, 0
	v_mbcnt_hi_u32_b32 v1, -1, v1
	v_and_b32_e32 v2, 64, v1
	v_add_u32_e32 v2, 64, v2
	s_waitcnt lgkmcnt(0)
	v_xor_b32_e32 v3, 1, v1
	v_cmp_lt_i32_e32 vcc, v3, v2
	s_lshl_b32 s8, s97, 3
	s_mov_b64 s[0:1], 0x1000
	v_cndmask_b32_e32 v3, v1, v3, vcc
	v_lshlrev_b32_e32 v52, 2, v3
	v_xor_b32_e32 v3, 2, v1
	v_cmp_lt_i32_e32 vcc, v3, v2
	s_add_u32 s9, s86, 0x40000
	s_addc_u32 s10, s87, 0
	v_cndmask_b32_e32 v3, v1, v3, vcc
	v_lshlrev_b32_e32 v53, 2, v3
	v_xor_b32_e32 v3, 4, v1
	v_cmp_lt_i32_e32 vcc, v3, v2
	s_add_u32 s11, s86, 0x16e00000
	s_mov_b32 s5, 0
	v_cndmask_b32_e32 v3, v1, v3, vcc
	v_lshlrev_b32_e32 v54, 2, v3
	v_xor_b32_e32 v3, 8, v1
	v_cmp_lt_i32_e32 vcc, v3, v2
	s_addc_u32 s12, s87, 0
	s_movk_i32 s13, 0x4000
	v_cndmask_b32_e32 v3, v1, v3, vcc
	v_lshlrev_b32_e32 v55, 2, v3
	v_xor_b32_e32 v3, 16, v1
	v_cmp_lt_i32_e32 vcc, v3, v2
	s_movk_i32 s14, 0x2000
	s_movk_i32 s15, 0x6000
	v_cndmask_b32_e32 v3, v1, v3, vcc
	v_lshlrev_b32_e32 v56, 2, v3
	v_xor_b32_e32 v3, 32, v1
	v_cmp_lt_i32_e32 vcc, v3, v2
	v_bfe_u32 v2, v0, 5, 1
	s_mov_b32 s16, 0x8000
	v_cndmask_b32_e32 v1, v1, v3, vcc
	v_lshlrev_b32_e32 v57, 2, v1
	v_lshlrev_b32_e32 v1, 2, v0
	v_lshrrev_b32_e32 v0, 2, v0
	v_and_or_b32 v0, v0, 6, v2
	v_mov_b32_e32 v3, 0
	v_lshlrev_b32_e32 v2, 4, v182
	v_lshl_add_u64 v[4:5], s[50:51], 0, v[2:3]
	v_lshl_add_u64 v[6:7], v[4:5], 0, s[0:1]
	s_mov_b64 s[0:1], 0x1400
	v_lshl_add_u64 v[8:9], v[4:5], 0, s[0:1]
	s_mov_b64 s[0:1], 0x1800
	v_lshl_add_u64 v[10:11], v[4:5], 0, s[0:1]
	s_mov_b64 s[0:1], 0x1c00
	v_and_b32_e32 v58, 28, v1
	v_lshlrev_b32_e32 v0, 10, v0
	v_mov_b32_e32 v1, v3
	v_lshl_add_u64 v[12:13], v[4:5], 0, s[0:1]
	v_lshl_add_u64 v[14:15], s[84:85], 0, v[2:3]
	v_lshl_add_u64 v[16:17], s[86:87], 0, v[2:3]
	s_mov_b32 s17, 0xa000
	s_mov_b32 s18, 0xc000
	s_mov_b32 s19, 0x1b400000
	s_mov_b32 s20, 0x1b401000
	s_mov_b32 s21, 0x1b800000
	s_mov_b32 s22, 0x1b801000
	s_mov_b32 s23, 0x1bc00000
	s_mov_b32 s24, 0x1bc01000
	s_brev_b32 s25, 56
	s_mov_b32 s26, 0x1c001000
	v_mov_b32_e32 v59, 0x358637bd
	s_mov_b32 s27, 0xf800000
	v_mov_b32_e32 v60, 0x260
	s_movk_i32 s28, 0x1000
	global_load_dwordx4 v[192:195], v[4:5], off
	global_load_dwordx4 v[196:199], v[4:5], off offset:1024
	global_load_dwordx4 v[200:203], v[4:5], off offset:2048
	global_load_dwordx4 v[204:207], v[4:5], off offset:3072
	global_load_dwordx4 v[208:211], v[6:7], off
	global_load_dwordx4 v[212:215], v[8:9], off
	global_load_dwordx4 v[216:219], v[10:11], off
	global_load_dwordx4 v[220:223], v[12:13], off
	s_branch .LBB0_2484
.LBB0_2483:
	v_fmamk_f32 v2, v2, 0x3a000000, v59
	v_mul_f32_e32 v50, 0x4f800000, v2
	v_cmp_gt_f32_e32 vcc, s27, v2
	s_lshl_b64 s[6:7], s[2:3], 13
	s_add_i32 s2, s2, s8
	v_cndmask_b32_e32 v2, v2, v50, vcc
	v_sqrt_f32_e32 v50, v2
	s_cmpk_lt_i32 s2, 0x4200
	s_waitcnt lgkmcnt(0)
	v_add_u32_e32 v51, -1, v50
	v_add_u32_e32 v61, 1, v50
	v_fma_f32 v66, -v51, v50, v2
	v_fma_f32 v67, -v61, v50, v2
	v_cmp_ge_f32_e64 s[0:1], 0, v66
	s_nop 1
	v_cndmask_b32_e64 v50, v50, v51, s[0:1]
	v_cmp_lt_f32_e64 s[0:1], 0, v67
	s_nop 1
	v_cndmask_b32_e64 v50, v50, v61, s[0:1]
	v_mul_f32_e32 v51, 0x37800000, v50
	v_cndmask_b32_e32 v50, v50, v51, vcc
	v_cmp_class_f32_e32 vcc, v2, v60
	s_nop 1
	v_cndmask_b32_e32 v2, v50, v2, vcc
	v_div_scale_f32 v61, s[0:1], v2, v2, 1.0
	v_rcp_f32_e32 v66, v61
	v_div_scale_f32 v67, vcc, 1.0, v2, 1.0
	v_lshl_add_u64 v[50:51], v[14:15], 0, s[6:7]
	v_fma_f32 v68, -v61, v66, 1.0
	v_fmac_f32_e32 v66, v68, v66
	v_mul_f32_e32 v68, v67, v66
	v_fma_f32 v69, -v61, v68, v67
	v_fmac_f32_e32 v68, v69, v66
	v_fma_f32 v61, -v61, v68, v67
	v_div_fmas_f32 v61, v61, v66, v68
	v_div_fixup_f32 v2, v61, v2, 1.0
	v_pk_mul_f32 v[46:47], v[46:47], v[2:3] op_sel_hi:[1,0]
	v_pk_mul_f32 v[48:49], v[48:49], v[2:3] op_sel_hi:[1,0]
	v_pk_mul_f32 v[44:45], v[44:45], v[2:3] op_sel_hi:[1,0]
	v_pk_mul_f32 v[42:43], v[42:43], v[2:3] op_sel_hi:[1,0]
	v_pk_mul_f32 v[40:41], v[40:41], v[2:3] op_sel_hi:[1,0]
	v_pk_mul_f32 v[38:39], v[38:39], v[2:3] op_sel_hi:[1,0]
	v_pk_mul_f32 v[36:37], v[36:37], v[2:3] op_sel_hi:[1,0]
	v_pk_mul_f32 v[34:35], v[34:35], v[2:3] op_sel_hi:[1,0]
	v_pk_mul_f32 v[32:33], v[32:33], v[2:3] op_sel_hi:[1,0]
	v_pk_mul_f32 v[30:31], v[30:31], v[2:3] op_sel_hi:[1,0]
	v_pk_mul_f32 v[28:29], v[28:29], v[2:3] op_sel_hi:[1,0]
	v_pk_mul_f32 v[26:27], v[26:27], v[2:3] op_sel_hi:[1,0]
	v_pk_mul_f32 v[24:25], v[24:25], v[2:3] op_sel_hi:[1,0]
	v_pk_mul_f32 v[22:23], v[22:23], v[2:3] op_sel_hi:[1,0]
	v_pk_mul_f32 v[20:21], v[20:21], v[2:3] op_sel_hi:[1,0]
	v_pk_mul_f32 v[18:19], v[18:19], v[2:3] op_sel_hi:[1,0]
	v_pk_mul_f32 v[48:49], v[194:195], v[48:49]
	v_pk_mul_f32 v[46:47], v[192:193], v[46:47]
	global_store_dwordx4 v[50:51], v[46:49], off nt
	v_pk_mul_f32 v[42:43], v[196:197], v[42:43]
	v_pk_mul_f32 v[44:45], v[198:199], v[44:45]
	global_store_dwordx4 v[50:51], v[42:45], off offset:1024 nt
	v_pk_mul_f32 v[38:39], v[200:201], v[38:39]
	v_pk_mul_f32 v[40:41], v[202:203], v[40:41]
	global_store_dwordx4 v[50:51], v[38:41], off offset:2048 nt
	v_pk_mul_f32 v[34:35], v[34:35], v[204:205]
	v_pk_mul_f32 v[36:37], v[36:37], v[206:207]
	global_store_dwordx4 v[50:51], v[34:37], off offset:3072 nt
	v_add_co_u32_e32 v38, vcc, s28, v50
	v_pk_mul_f32 v[30:31], v[30:31], v[208:209]
	v_addc_co_u32_e32 v39, vcc, 0, v51, vcc
	v_pk_mul_f32 v[32:33], v[32:33], v[210:211]
	global_store_dwordx4 v[38:39], v[30:33], off nt
	v_pk_mul_f32 v[26:27], v[26:27], v[212:213]
	v_pk_mul_f32 v[28:29], v[28:29], v[214:215]
	global_store_dwordx4 v[38:39], v[26:29], off offset:1024 nt
	v_pk_mul_f32 v[22:23], v[22:23], v[216:217]
	v_pk_mul_f32 v[24:25], v[24:25], v[218:219]
	global_store_dwordx4 v[38:39], v[22:25], off offset:2048 nt
	v_pk_mul_f32 v[18:19], v[18:19], v[220:221]
	v_pk_mul_f32 v[20:21], v[20:21], v[222:223]
	global_store_dwordx4 v[38:39], v[18:21], off offset:3072 nt
	s_cbranch_scc0 .LBB0_2493
